# adds input-GEMM gate epilogues (sigmoid): the 11-instruction IEEE sequence for 1.0f/(1+exp(-x)) replaced by v_rcp_f32 (f32, 1 ulp; result is rounded to bf16 next); 240 division chains per lane-unit re
# speedup vs baseline: 1.0160x; 1.0038x over previous
; __device__ __forceinline__ unsigned pk2(float lo, float hi) { f32x2 v = {lo, hi}; bf16x2_hw b = __builtin_convertvector(v, bf16x2_hw); return __builtin_bit_cast(unsigned, b); }
; __device__ __forceinline__ float sigm(float x) { return 1.f / (1.f + __expf(-x)); }
; __device__ __forceinline__ void st_bf8(bf16* p, f32x4 a, f32x4 b) { u32x4 w; w.x = pk2(a[0], a[1]); w.y = pk2(a[2], a[3]); w.z = pk2(b[0], b[1]); w.w = pk2(b[2], b[3]); *(u32x4*)p = w; }
; __device__ __forceinline__ void ld_bf8(const bf16* p, f32x4& a, f32x4& b) { const u32x4 w = *(const u32x4*)p; a = (f32x4){bflo(w.x), bfhi(w.x), bflo(w.y), bfhi(w.y)}; b = (f32x4){bflo(w.z), bfhi(w.z), bflo(w.w), bfhi(w.w)}; }
; __device__ __forceinline__ f32x4 sigm4(f32x4 v) { return (f32x4){sigm(v[0]), sigm(v[1]), sigm(v[2]), sigm(v[3])}; }
;     __device__ __forceinline__ void operator()(AccRef acc, const pg8::Unit& u, int wr, int wc, int fr, int fq) const {
;     ...
;         else if (t < 19) { const int c0 = (t - 15) * 256; EPI_LOOP_P( st_bf8(GD + rw * 1024 + c0 + cl, sigm4(v0), sigm4(v1)); ) }
;         else { const int c0 = (t - 19) * 256; EPI_LOOP_P( st_bf8(GM + rw * 1024 + c0 + cl, sigm4(v0), sigm4(v1)); ) }
.LBB0_792:
	s_cmp_gt_u32 s75, 7
	s_cbranch_scc0 .LBB0_838
	s_cmp_gt_u32 s75, 11
	s_cbranch_scc0 .LBB0_803
	s_cmp_gt_u32 s75, 14
	s_cbranch_scc0 .LBB0_800
	v_mul_f32_e32 v128, 0xbfb8aa3b, v124
	v_mul_f32_e32 v129, 0xbfb8aa3b, v125
	v_exp_f32_e32 v128, v128
	v_exp_f32_e32 v129, v129
	v_mul_f32_e32 v161, 0xbfb8aa3b, v101
	v_mul_f32_e32 v162, 0xbfb8aa3b, v102
	v_mul_f32_e32 v163, 0xbfb8aa3b, v103
	v_pk_add_f32 v[128:129], v[128:129], 1.0 op_sel_hi:[1,0]
	v_mul_f32_e32 v164, 0xbfb8aa3b, v96
	v_mul_f32_e32 v165, 0xbfb8aa3b, v97
	v_mul_f32_e32 v178, 0xbfb8aa3b, v98
	v_mul_f32_e32 v179, 0xbfb8aa3b, v99
	v_rcp_f32_e32 v130, v129
	v_mul_f32_e32 v184, 0xbfb8aa3b, v92
	v_mul_f32_e32 v194, 0xbfb8aa3b, v93
	v_mul_f32_e32 v196, 0xbfb8aa3b, v94
	v_rcp_f32_e32 v131, v128
	v_mul_f32_e32 v128, 0xbfb8aa3b, v126
	v_mul_f32_e32 v129, 0xbfb8aa3b, v127
	v_exp_f32_e32 v128, v128
	v_exp_f32_e32 v129, v129
	v_mul_f32_e32 v197, 0xbfb8aa3b, v95
	v_mul_f32_e32 v198, 0xbfb8aa3b, v88
	v_mul_f32_e32 v199, 0xbfb8aa3b, v89
	v_pk_add_f32 v[128:129], v[128:129], 1.0 op_sel_hi:[1,0]
	v_mul_f32_e32 v200, 0xbfb8aa3b, v90
	v_mul_f32_e32 v201, 0xbfb8aa3b, v91
	v_mul_f32_e32 v202, 0xbfb8aa3b, v84
	v_mul_f32_e32 v203, 0xbfb8aa3b, v85
	v_rcp_f32_e32 v132, v129
	v_exp_f32_e32 v169, v161
	v_exp_f32_e32 v166, v162
	v_exp_f32_e32 v167, v163
	v_rcp_f32_e32 v133, v128
	v_mul_f32_e32 v128, 0xbfb8aa3b, v120
	v_mul_f32_e32 v129, 0xbfb8aa3b, v121
	v_exp_f32_e32 v128, v128
	v_exp_f32_e32 v129, v129
	v_exp_f32_e32 v164, v164
	v_exp_f32_e32 v165, v165
	v_exp_f32_e32 v162, v178
	v_pk_add_f32 v[128:129], v[128:129], 1.0 op_sel_hi:[1,0]
	v_exp_f32_e32 v163, v179
	v_exp_f32_e32 v161, v194
	s_lshl_b32 s66, s75, 8
	s_cmp_gt_u32 s75, 18
	v_rcp_f32_e32 v134, v129
	v_mul_f32_e32 v194, 0xbfb8aa3b, v82
	v_rcp_f32_e32 v135, v128
	v_mul_f32_e32 v128, 0xbfb8aa3b, v122
	v_mul_f32_e32 v129, 0xbfb8aa3b, v123
	v_exp_f32_e32 v128, v128
	v_exp_f32_e32 v129, v129
	s_nop 0
	v_pk_add_f32 v[128:129], v[128:129], 1.0 op_sel_hi:[1,0]
	s_nop 0
	v_rcp_f32_e32 v152, v129
	v_rcp_f32_e32 v153, v128
	v_cvt_pk_bf16_f32 v129, v133, v132
	v_mul_f32_e32 v132, 0xbfb8aa3b, v116
	v_mul_f32_e32 v133, 0xbfb8aa3b, v117
	v_exp_f32_e32 v132, v132
	v_exp_f32_e32 v133, v133
	v_cvt_pk_bf16_f32 v128, v131, v130
	v_cvt_pk_bf16_f32 v130, v135, v134
	v_cvt_pk_bf16_f32 v131, v153, v152
	v_pk_add_f32 v[132:133], v[132:133], 1.0 op_sel_hi:[1,0]
	s_nop 0
	v_rcp_f32_e32 v134, v133
	v_rcp_f32_e32 v135, v132
	v_mul_f32_e32 v132, 0xbfb8aa3b, v118
	v_mul_f32_e32 v133, 0xbfb8aa3b, v119
	v_exp_f32_e32 v132, v132
	v_exp_f32_e32 v133, v133
	s_nop 0
	v_pk_add_f32 v[132:133], v[132:133], 1.0 op_sel_hi:[1,0]
	s_nop 0
	v_rcp_f32_e32 v152, v133
	v_rcp_f32_e32 v153, v132
	v_mul_f32_e32 v132, 0xbfb8aa3b, v112
	v_mul_f32_e32 v133, 0xbfb8aa3b, v113
	v_exp_f32_e32 v132, v132
	v_exp_f32_e32 v133, v133
	s_nop 0
	v_pk_add_f32 v[132:133], v[132:133], 1.0 op_sel_hi:[1,0]
	s_nop 0
	v_rcp_f32_e32 v154, v133
	v_rcp_f32_e32 v155, v132
	v_mul_f32_e32 v132, 0xbfb8aa3b, v114
	v_mul_f32_e32 v133, 0xbfb8aa3b, v115
	v_exp_f32_e32 v132, v132
	v_exp_f32_e32 v133, v133
	s_nop 0
	v_pk_add_f32 v[132:133], v[132:133], 1.0 op_sel_hi:[1,0]
	s_nop 0
	v_rcp_f32_e32 v156, v133
	s_mov_b64 s[22:23], -1
	v_rcp_f32_e32 v157, v132
	v_cvt_pk_bf16_f32 v132, v135, v134
	v_cvt_pk_bf16_f32 v133, v153, v152
	v_cvt_pk_bf16_f32 v134, v155, v154
	v_cvt_pk_bf16_f32 v135, v157, v156
	v_mul_f32_e32 v152, 0xbfb8aa3b, v108
	v_mul_f32_e32 v153, 0xbfb8aa3b, v109
	v_mul_f32_e32 v154, 0xbfb8aa3b, v110
	v_mul_f32_e32 v155, 0xbfb8aa3b, v111
	v_mul_f32_e32 v156, 0xbfb8aa3b, v104
	v_mul_f32_e32 v157, 0xbfb8aa3b, v105
	v_mul_f32_e32 v158, 0xbfb8aa3b, v106
	v_mul_f32_e32 v159, 0xbfb8aa3b, v107
	v_mul_f32_e32 v160, 0xbfb8aa3b, v100
	v_exp_f32_e32 v176, v152
	v_exp_f32_e32 v177, v153
	v_exp_f32_e32 v174, v154
	v_exp_f32_e32 v175, v155
	v_exp_f32_e32 v172, v156
	v_exp_f32_e32 v173, v157
	v_exp_f32_e32 v170, v158
	v_exp_f32_e32 v171, v159
	v_exp_f32_e32 v168, v160
	v_exp_f32_e32 v160, v184
	v_exp_f32_e32 v158, v196
	v_exp_f32_e32 v159, v197
	v_exp_f32_e32 v156, v198
	v_exp_f32_e32 v157, v199
	v_exp_f32_e32 v154, v200
	v_exp_f32_e32 v155, v201
	v_exp_f32_e32 v152, v202
	v_exp_f32_e32 v153, v203
	v_mul_f32_e32 v199, 0xbfb8aa3b, v86
	v_mul_f32_e32 v200, 0xbfb8aa3b, v87
	v_mul_f32_e32 v197, 0xbfb8aa3b, v80
	v_mul_f32_e32 v198, 0xbfb8aa3b, v81
	v_mul_f32_e32 v196, 0xbfb8aa3b, v83
	s_cbranch_scc0 .LBB0_797
; __device__ __forceinline__ unsigned pk2(float lo, float hi) { f32x2 v = {lo, hi}; bf16x2_hw b = __builtin_convertvector(v, bf16x2_hw); return __builtin_bit_cast(unsigned, b); }
; __device__ __forceinline__ float sigm(float x) { return 1.f / (1.f + __expf(-x)); }
; __device__ __forceinline__ void st_bf8(bf16* p, f32x4 a, f32x4 b) { u32x4 w; w.x = pk2(a[0], a[1]); w.y = pk2(a[2], a[3]); w.z = pk2(b[0], b[1]); w.w = pk2(b[2], b[3]); *(u32x4*)p = w; }
; __device__ __forceinline__ void ld_bf8(const bf16* p, f32x4& a, f32x4& b) { const u32x4 w = *(const u32x4*)p; a = (f32x4){bflo(w.x), bfhi(w.x), bflo(w.y), bfhi(w.y)}; b = (f32x4){bflo(w.z), bfhi(w.z), bflo(w.w), bfhi(w.w)}; }
; __device__ __forceinline__ f32x4 sigm4(f32x4 v) { return (f32x4){sigm(v[0]), sigm(v[1]), sigm(v[2]), sigm(v[3])}; }
;     __device__ __forceinline__ void operator()(AccRef acc, const pg8::Unit& u, int wr, int wc, int fr, int fq) const {
;     ...
;         else if (t < 19) { const int c0 = (t - 15) * 256; EPI_LOOP_P( st_bf8(GD + rw * 1024 + c0 + cl, sigm4(v0), sigm4(v1)); ) }
;         else { const int c0 = (t - 19) * 256; EPI_LOOP_P( st_bf8(GM + rw * 1024 + c0 + cl, sigm4(v0), sigm4(v1)); ) }
	v_pk_add_f32 v[202:203], v[176:177], 1.0 op_sel_hi:[1,0]
	s_lshl_b32 s22, s74, 8
	v_add_u32_e32 v178, s22, v145
	v_ashrrev_i32_e32 v179, 31, v178
	s_add_i32 s38, s66, 0xffffed00
	v_rcp_f32_e32 v201, v203
	s_mov_b32 s39, s67
	v_lshlrev_b64 v[178:179], 11, v[178:179]
	v_lshl_add_u64 v[178:179], s[28:29], 0, v[178:179]
	v_rcp_f32_e32 v212, v202
	v_pk_add_f32 v[202:203], v[174:175], 1.0 op_sel_hi:[1,0]
	s_lshl_b64 s[38:39], s[38:39], 1
	v_lshl_add_u64 v[178:179], v[178:179], 0, s[38:39]
	v_lshlrev_b32_e32 v184, 1, v144
	v_lshl_add_u64 v[178:179], v[178:179], 0, v[184:185]
	v_rcp_f32_e32 v213, v203
	global_store_dwordx4 v[178:179], v[128:131], off
	global_store_dwordx4 v[178:179], v[132:135], off offset:256
	v_add_u32_e32 v178, s22, v180
	v_ashrrev_i32_e32 v179, 31, v178
	v_rcp_f32_e32 v214, v202
	v_pk_add_f32 v[202:203], v[172:173], 1.0 op_sel_hi:[1,0]
	v_lshlrev_b64 v[178:179], 11, v[178:179]
	v_lshl_add_u64 v[178:179], s[28:29], 0, v[178:179]
	v_lshl_add_u64 v[178:179], v[178:179], 0, s[38:39]
	v_cvt_pk_bf16_f32 v213, v214, v213
	v_rcp_f32_e32 v215, v203
	v_lshl_add_u64 v[178:179], v[178:179], 0, v[184:185]
	v_cvt_pk_bf16_f32 v212, v212, v201
	v_rcp_f32_e32 v216, v202
	v_pk_add_f32 v[202:203], v[170:171], 1.0 op_sel_hi:[1,0]
	v_cvt_pk_bf16_f32 v214, v216, v215
	v_rcp_f32_e32 v203, v203
	v_rcp_f32_e32 v202, v202
	s_nop 0
	v_cvt_pk_bf16_f32 v215, v202, v203
	v_pk_add_f32 v[202:203], v[168:169], 1.0 op_sel_hi:[1,0]
	global_store_dwordx4 v[178:179], v[212:215], off
	s_nop 1
	v_rcp_f32_e32 v201, v203
	v_rcp_f32_e32 v212, v202
	v_pk_add_f32 v[202:203], v[166:167], 1.0 op_sel_hi:[1,0]
	v_cvt_pk_bf16_f32 v212, v212, v201
	v_rcp_f32_e32 v213, v203
	v_rcp_f32_e32 v214, v202
	v_pk_add_f32 v[202:203], v[164:165], 1.0 op_sel_hi:[1,0]
	v_cvt_pk_bf16_f32 v213, v214, v213
	v_rcp_f32_e32 v215, v203
	v_rcp_f32_e32 v216, v202
	v_pk_add_f32 v[202:203], v[162:163], 1.0 op_sel_hi:[1,0]
	v_cvt_pk_bf16_f32 v214, v216, v215
	v_rcp_f32_e32 v203, v203
	v_rcp_f32_e32 v202, v202
	s_nop 0
	v_cvt_pk_bf16_f32 v215, v202, v203
	v_pk_add_f32 v[202:203], v[160:161], 1.0 op_sel_hi:[1,0]
	global_store_dwordx4 v[178:179], v[212:215], off offset:256
	v_add_u32_e32 v178, s22, v181
	v_ashrrev_i32_e32 v179, 31, v178
	v_lshlrev_b64 v[178:179], 11, v[178:179]
	v_rcp_f32_e32 v201, v203
	v_lshl_add_u64 v[178:179], s[28:29], 0, v[178:179]
	v_lshl_add_u64 v[178:179], v[178:179], 0, s[38:39]
	v_lshl_add_u64 v[178:179], v[178:179], 0, v[184:185]
	v_rcp_f32_e32 v212, v202
	v_pk_add_f32 v[202:203], v[158:159], 1.0 op_sel_hi:[1,0]
	v_cvt_pk_bf16_f32 v212, v212, v201
	v_rcp_f32_e32 v213, v203
	v_rcp_f32_e32 v214, v202
	v_pk_add_f32 v[202:203], v[156:157], 1.0 op_sel_hi:[1,0]
	v_cvt_pk_bf16_f32 v213, v214, v213
	v_rcp_f32_e32 v215, v203
	v_rcp_f32_e32 v216, v202
	v_pk_add_f32 v[202:203], v[154:155], 1.0 op_sel_hi:[1,0]
	v_cvt_pk_bf16_f32 v214, v216, v215
	v_rcp_f32_e32 v203, v203
	v_rcp_f32_e32 v202, v202
	s_nop 0
	v_cvt_pk_bf16_f32 v215, v202, v203
	v_pk_add_f32 v[202:203], v[152:153], 1.0 op_sel_hi:[1,0]
	global_store_dwordx4 v[178:179], v[212:215], off
	s_nop 1
	v_rcp_f32_e32 v201, v203
	v_rcp_f32_e32 v212, v202
	v_exp_f32_e32 v202, v199
	v_exp_f32_e32 v203, v200
	v_cvt_pk_bf16_f32 v212, v212, v201
	v_mul_f32_e32 v201, 0xbfb8aa3b, v76
	v_pk_add_f32 v[202:203], v[202:203], 1.0 op_sel_hi:[1,0]
	s_nop 0
	v_rcp_f32_e32 v213, v203
	v_rcp_f32_e32 v214, v202
	v_exp_f32_e32 v202, v197
	v_exp_f32_e32 v203, v198
	v_cvt_pk_bf16_f32 v213, v214, v213
	v_pk_add_f32 v[202:203], v[202:203], 1.0 op_sel_hi:[1,0]
	s_nop 0
	v_rcp_f32_e32 v215, v203
	v_rcp_f32_e32 v216, v202
	v_exp_f32_e32 v202, v194
	v_exp_f32_e32 v203, v196
	v_cvt_pk_bf16_f32 v214, v216, v215
	v_pk_add_f32 v[202:203], v[202:203], 1.0 op_sel_hi:[1,0]
	s_nop 0
	v_rcp_f32_e32 v203, v203
	v_rcp_f32_e32 v202, v202
	s_nop 0
	v_cvt_pk_bf16_f32 v215, v202, v203
	v_exp_f32_e32 v202, v201
	v_mul_f32_e32 v201, 0xbfb8aa3b, v77
	v_exp_f32_e32 v203, v201
	global_store_dwordx4 v[178:179], v[212:215], off offset:256
	v_add_u32_e32 v178, s22, v182
	v_ashrrev_i32_e32 v179, 31, v178
	v_pk_add_f32 v[202:203], v[202:203], 1.0 op_sel_hi:[1,0]
	v_lshlrev_b64 v[178:179], 11, v[178:179]
	v_lshl_add_u64 v[178:179], s[28:29], 0, v[178:179]
	v_lshl_add_u64 v[178:179], v[178:179], 0, s[38:39]
	v_lshl_add_u64 v[178:179], v[178:179], 0, v[184:185]
	v_rcp_f32_e32 v201, v203
	v_rcp_f32_e32 v212, v202
	v_mul_f32_e32 v202, 0xbfb8aa3b, v78
	v_mul_f32_e32 v203, 0xbfb8aa3b, v79
	v_exp_f32_e32 v202, v202
	v_exp_f32_e32 v203, v203
	v_cvt_pk_bf16_f32 v212, v212, v201
	v_mul_f32_e32 v201, 0xbfb8aa3b, v68
	v_pk_add_f32 v[202:203], v[202:203], 1.0 op_sel_hi:[1,0]
	s_nop 0
	v_rcp_f32_e32 v213, v203
	v_rcp_f32_e32 v214, v202
	v_mul_f32_e32 v202, 0xbfb8aa3b, v72
	v_mul_f32_e32 v203, 0xbfb8aa3b, v73
	v_exp_f32_e32 v202, v202
	v_exp_f32_e32 v203, v203
	v_cvt_pk_bf16_f32 v213, v214, v213
	v_pk_add_f32 v[202:203], v[202:203], 1.0 op_sel_hi:[1,0]
	s_nop 0
	v_rcp_f32_e32 v215, v203
	v_rcp_f32_e32 v216, v202
	v_mul_f32_e32 v202, 0xbfb8aa3b, v74
	v_mul_f32_e32 v203, 0xbfb8aa3b, v75
	v_exp_f32_e32 v202, v202
	v_exp_f32_e32 v203, v203
	v_cvt_pk_bf16_f32 v214, v216, v215
	v_pk_add_f32 v[202:203], v[202:203], 1.0 op_sel_hi:[1,0]
	s_nop 0
	v_rcp_f32_e32 v203, v203
	v_rcp_f32_e32 v202, v202
	s_nop 0
	v_cvt_pk_bf16_f32 v215, v202, v203
	v_exp_f32_e32 v202, v201
	v_mul_f32_e32 v201, 0xbfb8aa3b, v69
	v_exp_f32_e32 v203, v201
	global_store_dwordx4 v[178:179], v[212:215], off
	v_pk_add_f32 v[202:203], v[202:203], 1.0 op_sel_hi:[1,0]
	s_nop 0
	v_rcp_f32_e32 v201, v203
	v_rcp_f32_e32 v212, v202
	v_mul_f32_e32 v202, 0xbfb8aa3b, v70
	v_mul_f32_e32 v203, 0xbfb8aa3b, v71
	v_exp_f32_e32 v202, v202
; __device__ __forceinline__ unsigned pk2(float lo, float hi) { f32x2 v = {lo, hi}; bf16x2_hw b = __builtin_convertvector(v, bf16x2_hw); return __builtin_bit_cast(unsigned, b); }
; __device__ __forceinline__ float sigm(float x) { return 1.f / (1.f + __expf(-x)); }
; __device__ __forceinline__ void st_bf8(bf16* p, f32x4 a, f32x4 b) { u32x4 w; w.x = pk2(a[0], a[1]); w.y = pk2(a[2], a[3]); w.z = pk2(b[0], b[1]); w.w = pk2(b[2], b[3]); *(u32x4*)p = w; }
; __device__ __forceinline__ void ld_bf8(const bf16* p, f32x4& a, f32x4& b) { const u32x4 w = *(const u32x4*)p; a = (f32x4){bflo(w.x), bfhi(w.x), bflo(w.y), bfhi(w.y)}; b = (f32x4){bflo(w.z), bfhi(w.z), bflo(w.w), bfhi(w.w)}; }
; __device__ __forceinline__ f32x4 sigm4(f32x4 v) { return (f32x4){sigm(v[0]), sigm(v[1]), sigm(v[2]), sigm(v[3])}; }
;     __device__ __forceinline__ void operator()(AccRef acc, const pg8::Unit& u, int wr, int wc, int fr, int fq) const {
;     ...
;         else if (t < 19) { const int c0 = (t - 15) * 256; EPI_LOOP_P( st_bf8(GD + rw * 1024 + c0 + cl, sigm4(v0), sigm4(v1)); ) }
;         else { const int c0 = (t - 19) * 256; EPI_LOOP_P( st_bf8(GM + rw * 1024 + c0 + cl, sigm4(v0), sigm4(v1)); ) }
	v_exp_f32_e32 v203, v203
	v_cvt_pk_bf16_f32 v212, v212, v201
	v_mul_f32_e32 v201, 0xbfb8aa3b, v60
	v_pk_add_f32 v[202:203], v[202:203], 1.0 op_sel_hi:[1,0]
	s_nop 0
	v_rcp_f32_e32 v213, v203
	v_rcp_f32_e32 v214, v202
	v_mul_f32_e32 v202, 0xbfb8aa3b, v64
	v_mul_f32_e32 v203, 0xbfb8aa3b, v65
	v_exp_f32_e32 v202, v202
	v_exp_f32_e32 v203, v203
	v_cvt_pk_bf16_f32 v213, v214, v213
	v_pk_add_f32 v[202:203], v[202:203], 1.0 op_sel_hi:[1,0]
	s_nop 0
	v_rcp_f32_e32 v215, v203
	v_rcp_f32_e32 v216, v202
	v_mul_f32_e32 v202, 0xbfb8aa3b, v66
	v_mul_f32_e32 v203, 0xbfb8aa3b, v67
	v_exp_f32_e32 v202, v202
	v_exp_f32_e32 v203, v203
	v_cvt_pk_bf16_f32 v214, v216, v215
	v_pk_add_f32 v[202:203], v[202:203], 1.0 op_sel_hi:[1,0]
	s_nop 0
	v_rcp_f32_e32 v203, v203
	v_rcp_f32_e32 v202, v202
	s_nop 0
	v_cvt_pk_bf16_f32 v215, v202, v203
	v_exp_f32_e32 v202, v201
	v_mul_f32_e32 v201, 0xbfb8aa3b, v61
	v_exp_f32_e32 v203, v201
	global_store_dwordx4 v[178:179], v[212:215], off offset:256
	v_add_u32_e32 v178, s22, v183
	v_ashrrev_i32_e32 v179, 31, v178
	v_pk_add_f32 v[202:203], v[202:203], 1.0 op_sel_hi:[1,0]
	v_lshlrev_b64 v[178:179], 11, v[178:179]
	v_lshl_add_u64 v[178:179], s[28:29], 0, v[178:179]
	v_lshl_add_u64 v[178:179], v[178:179], 0, s[38:39]
	v_lshl_add_u64 v[178:179], v[178:179], 0, v[184:185]
	v_rcp_f32_e32 v201, v203
	v_rcp_f32_e32 v212, v202
	v_mul_f32_e32 v202, 0xbfb8aa3b, v62
	v_mul_f32_e32 v203, 0xbfb8aa3b, v63
	v_exp_f32_e32 v202, v202
	v_exp_f32_e32 v203, v203
	v_cvt_pk_bf16_f32 v212, v212, v201
	v_mul_f32_e32 v201, 0xbfb8aa3b, v52
	v_pk_add_f32 v[202:203], v[202:203], 1.0 op_sel_hi:[1,0]
	s_nop 0
	v_rcp_f32_e32 v213, v203
	v_rcp_f32_e32 v214, v202
	v_mul_f32_e32 v202, 0xbfb8aa3b, v56
	v_mul_f32_e32 v203, 0xbfb8aa3b, v57
	v_exp_f32_e32 v202, v202
	v_exp_f32_e32 v203, v203
	v_cvt_pk_bf16_f32 v213, v214, v213
	v_pk_add_f32 v[202:203], v[202:203], 1.0 op_sel_hi:[1,0]
	s_nop 0
	v_rcp_f32_e32 v215, v203
	v_rcp_f32_e32 v216, v202
	v_mul_f32_e32 v202, 0xbfb8aa3b, v58
	v_mul_f32_e32 v203, 0xbfb8aa3b, v59
	v_exp_f32_e32 v202, v202
	v_exp_f32_e32 v203, v203
	v_cvt_pk_bf16_f32 v214, v216, v215
	v_pk_add_f32 v[202:203], v[202:203], 1.0 op_sel_hi:[1,0]
	s_nop 0
	v_rcp_f32_e32 v203, v203
	v_rcp_f32_e32 v202, v202
	s_nop 0
	v_cvt_pk_bf16_f32 v215, v202, v203
	v_exp_f32_e32 v202, v201
	v_mul_f32_e32 v201, 0xbfb8aa3b, v53
	v_exp_f32_e32 v203, v201
	global_store_dwordx4 v[178:179], v[212:215], off
	v_pk_add_f32 v[202:203], v[202:203], 1.0 op_sel_hi:[1,0]
	s_nop 0
	v_rcp_f32_e32 v201, v203
	v_rcp_f32_e32 v212, v202
	v_mul_f32_e32 v202, 0xbfb8aa3b, v54
	v_mul_f32_e32 v203, 0xbfb8aa3b, v55
	v_exp_f32_e32 v202, v202
	v_exp_f32_e32 v203, v203
	v_cvt_pk_bf16_f32 v212, v212, v201
	v_mul_f32_e32 v201, 0xbfb8aa3b, v44
	v_pk_add_f32 v[202:203], v[202:203], 1.0 op_sel_hi:[1,0]
	s_nop 0
	v_rcp_f32_e32 v213, v203
	v_rcp_f32_e32 v214, v202
	v_mul_f32_e32 v202, 0xbfb8aa3b, v48
	v_mul_f32_e32 v203, 0xbfb8aa3b, v49
	v_exp_f32_e32 v202, v202
	v_exp_f32_e32 v203, v203
	v_cvt_pk_bf16_f32 v213, v214, v213
	v_pk_add_f32 v[202:203], v[202:203], 1.0 op_sel_hi:[1,0]
	s_nop 0
	v_rcp_f32_e32 v215, v203
	v_rcp_f32_e32 v216, v202
	v_mul_f32_e32 v202, 0xbfb8aa3b, v50
	v_mul_f32_e32 v203, 0xbfb8aa3b, v51
	v_exp_f32_e32 v202, v202
	v_exp_f32_e32 v203, v203
	v_cvt_pk_bf16_f32 v214, v216, v215
	v_pk_add_f32 v[202:203], v[202:203], 1.0 op_sel_hi:[1,0]
	s_nop 0
	v_rcp_f32_e32 v203, v203
	v_rcp_f32_e32 v202, v202
	s_nop 0
	v_cvt_pk_bf16_f32 v215, v202, v203
	v_exp_f32_e32 v202, v201
	v_mul_f32_e32 v201, 0xbfb8aa3b, v45
	v_exp_f32_e32 v203, v201
	global_store_dwordx4 v[178:179], v[212:215], off offset:256
	v_add_u32_e32 v178, s22, v190
	v_ashrrev_i32_e32 v179, 31, v178
	v_pk_add_f32 v[202:203], v[202:203], 1.0 op_sel_hi:[1,0]
	v_lshlrev_b64 v[178:179], 11, v[178:179]
	v_lshl_add_u64 v[178:179], s[28:29], 0, v[178:179]
	v_lshl_add_u64 v[178:179], v[178:179], 0, s[38:39]
	v_lshl_add_u64 v[178:179], v[178:179], 0, v[184:185]
	v_rcp_f32_e32 v201, v203
	v_rcp_f32_e32 v212, v202
	v_mul_f32_e32 v202, 0xbfb8aa3b, v46
	v_mul_f32_e32 v203, 0xbfb8aa3b, v47
	v_exp_f32_e32 v202, v202
	v_exp_f32_e32 v203, v203
	v_cvt_pk_bf16_f32 v212, v212, v201
	v_mul_f32_e32 v201, 0xbfb8aa3b, v36
	v_pk_add_f32 v[202:203], v[202:203], 1.0 op_sel_hi:[1,0]
	s_nop 0
	v_rcp_f32_e32 v213, v203
	v_rcp_f32_e32 v214, v202
	v_mul_f32_e32 v202, 0xbfb8aa3b, v40
	v_mul_f32_e32 v203, 0xbfb8aa3b, v41
	v_exp_f32_e32 v202, v202
	v_exp_f32_e32 v203, v203
	v_cvt_pk_bf16_f32 v213, v214, v213
	v_pk_add_f32 v[202:203], v[202:203], 1.0 op_sel_hi:[1,0]
	s_nop 0
	v_rcp_f32_e32 v215, v203
	v_rcp_f32_e32 v216, v202
	v_mul_f32_e32 v202, 0xbfb8aa3b, v42
	v_mul_f32_e32 v203, 0xbfb8aa3b, v43
	v_exp_f32_e32 v202, v202
	v_exp_f32_e32 v203, v203
	v_cvt_pk_bf16_f32 v214, v216, v215
	v_pk_add_f32 v[202:203], v[202:203], 1.0 op_sel_hi:[1,0]
	s_nop 0
	v_rcp_f32_e32 v203, v203
	v_rcp_f32_e32 v202, v202
	s_nop 0
	v_cvt_pk_bf16_f32 v215, v202, v203
	v_exp_f32_e32 v202, v201
	v_mul_f32_e32 v201, 0xbfb8aa3b, v37
	v_exp_f32_e32 v203, v201
	global_store_dwordx4 v[178:179], v[212:215], off
	v_pk_add_f32 v[202:203], v[202:203], 1.0 op_sel_hi:[1,0]
	s_nop 0
	v_rcp_f32_e32 v201, v203
	v_rcp_f32_e32 v212, v202
	v_mul_f32_e32 v202, 0xbfb8aa3b, v38
	v_mul_f32_e32 v203, 0xbfb8aa3b, v39
	v_exp_f32_e32 v202, v202
	v_exp_f32_e32 v203, v203
	v_cvt_pk_bf16_f32 v212, v212, v201
	v_mul_f32_e32 v201, 0xbfb8aa3b, v28
	v_pk_add_f32 v[202:203], v[202:203], 1.0 op_sel_hi:[1,0]
	s_nop 0
	v_rcp_f32_e32 v213, v203
	v_rcp_f32_e32 v214, v202
	v_mul_f32_e32 v202, 0xbfb8aa3b, v32
	v_mul_f32_e32 v203, 0xbfb8aa3b, v33
	v_exp_f32_e32 v202, v202
	v_exp_f32_e32 v203, v203
	v_cvt_pk_bf16_f32 v213, v214, v213
; __device__ __forceinline__ unsigned pk2(float lo, float hi) { f32x2 v = {lo, hi}; bf16x2_hw b = __builtin_convertvector(v, bf16x2_hw); return __builtin_bit_cast(unsigned, b); }
; __device__ __forceinline__ float sigm(float x) { return 1.f / (1.f + __expf(-x)); }
; __device__ __forceinline__ void st_bf8(bf16* p, f32x4 a, f32x4 b) { u32x4 w; w.x = pk2(a[0], a[1]); w.y = pk2(a[2], a[3]); w.z = pk2(b[0], b[1]); w.w = pk2(b[2], b[3]); *(u32x4*)p = w; }
; __device__ __forceinline__ void ld_bf8(const bf16* p, f32x4& a, f32x4& b) { const u32x4 w = *(const u32x4*)p; a = (f32x4){bflo(w.x), bfhi(w.x), bflo(w.y), bfhi(w.y)}; b = (f32x4){bflo(w.z), bfhi(w.z), bflo(w.w), bfhi(w.w)}; }
; __device__ __forceinline__ f32x4 sigm4(f32x4 v) { return (f32x4){sigm(v[0]), sigm(v[1]), sigm(v[2]), sigm(v[3])}; }
;     __device__ __forceinline__ void operator()(AccRef acc, const pg8::Unit& u, int wr, int wc, int fr, int fq) const {
;     ...
;         else if (t < 19) { const int c0 = (t - 15) * 256; EPI_LOOP_P( st_bf8(GD + rw * 1024 + c0 + cl, sigm4(v0), sigm4(v1)); ) }
;         else { const int c0 = (t - 19) * 256; EPI_LOOP_P( st_bf8(GM + rw * 1024 + c0 + cl, sigm4(v0), sigm4(v1)); ) }
	v_pk_add_f32 v[202:203], v[202:203], 1.0 op_sel_hi:[1,0]
	s_nop 0
	v_rcp_f32_e32 v215, v203
	v_rcp_f32_e32 v216, v202
	v_mul_f32_e32 v202, 0xbfb8aa3b, v34
	v_mul_f32_e32 v203, 0xbfb8aa3b, v35
	v_exp_f32_e32 v202, v202
	v_exp_f32_e32 v203, v203
	v_cvt_pk_bf16_f32 v214, v216, v215
	v_pk_add_f32 v[202:203], v[202:203], 1.0 op_sel_hi:[1,0]
	s_nop 0
	v_rcp_f32_e32 v203, v203
	v_rcp_f32_e32 v202, v202
	s_nop 0
	v_cvt_pk_bf16_f32 v215, v202, v203
	v_exp_f32_e32 v202, v201
	v_mul_f32_e32 v201, 0xbfb8aa3b, v29
	v_exp_f32_e32 v203, v201
	global_store_dwordx4 v[178:179], v[212:215], off offset:256
	v_add_u32_e32 v178, s22, v191
	v_ashrrev_i32_e32 v179, 31, v178
	v_pk_add_f32 v[202:203], v[202:203], 1.0 op_sel_hi:[1,0]
	v_lshlrev_b64 v[178:179], 11, v[178:179]
	v_lshl_add_u64 v[178:179], s[28:29], 0, v[178:179]
	v_lshl_add_u64 v[178:179], v[178:179], 0, s[38:39]
	v_lshl_add_u64 v[178:179], v[178:179], 0, v[184:185]
	v_rcp_f32_e32 v201, v203
	v_rcp_f32_e32 v212, v202
	v_mul_f32_e32 v202, 0xbfb8aa3b, v30
	v_mul_f32_e32 v203, 0xbfb8aa3b, v31
	v_exp_f32_e32 v202, v202
	v_exp_f32_e32 v203, v203
	v_cvt_pk_bf16_f32 v212, v212, v201
	v_mul_f32_e32 v201, 0xbfb8aa3b, v20
	v_pk_add_f32 v[202:203], v[202:203], 1.0 op_sel_hi:[1,0]
	s_nop 0
	v_rcp_f32_e32 v213, v203
	v_rcp_f32_e32 v214, v202
	v_mul_f32_e32 v202, 0xbfb8aa3b, v24
	v_mul_f32_e32 v203, 0xbfb8aa3b, v25
	v_exp_f32_e32 v202, v202
	v_exp_f32_e32 v203, v203
	v_cvt_pk_bf16_f32 v213, v214, v213
	v_pk_add_f32 v[202:203], v[202:203], 1.0 op_sel_hi:[1,0]
	s_nop 0
	v_rcp_f32_e32 v215, v203
	v_rcp_f32_e32 v216, v202
	v_mul_f32_e32 v202, 0xbfb8aa3b, v26
	v_mul_f32_e32 v203, 0xbfb8aa3b, v27
	v_exp_f32_e32 v202, v202
	v_exp_f32_e32 v203, v203
	v_cvt_pk_bf16_f32 v214, v216, v215
	v_pk_add_f32 v[202:203], v[202:203], 1.0 op_sel_hi:[1,0]
	s_nop 0
	v_rcp_f32_e32 v203, v203
	v_rcp_f32_e32 v202, v202
	s_nop 0
	v_cvt_pk_bf16_f32 v215, v202, v203
	v_exp_f32_e32 v202, v201
	v_mul_f32_e32 v201, 0xbfb8aa3b, v21
	v_exp_f32_e32 v203, v201
	global_store_dwordx4 v[178:179], v[212:215], off
	v_pk_add_f32 v[202:203], v[202:203], 1.0 op_sel_hi:[1,0]
	s_nop 0
	v_rcp_f32_e32 v201, v203
	v_rcp_f32_e32 v212, v202
	v_mul_f32_e32 v202, 0xbfb8aa3b, v22
	v_mul_f32_e32 v203, 0xbfb8aa3b, v23
	v_exp_f32_e32 v202, v202
	v_exp_f32_e32 v203, v203
	v_cvt_pk_bf16_f32 v212, v212, v201
	v_pk_add_f32 v[202:203], v[202:203], 1.0 op_sel_hi:[1,0]
	s_nop 0
	v_rcp_f32_e32 v213, v203
	v_rcp_f32_e32 v214, v202
	v_mul_f32_e32 v202, 0xbfb8aa3b, v16
	v_mul_f32_e32 v203, 0xbfb8aa3b, v17
	v_exp_f32_e32 v202, v202
	v_exp_f32_e32 v203, v203
	v_cvt_pk_bf16_f32 v213, v214, v213
	v_pk_add_f32 v[202:203], v[202:203], 1.0 op_sel_hi:[1,0]
	s_nop 0
	v_rcp_f32_e32 v215, v203
	v_rcp_f32_e32 v216, v202
	v_mul_f32_e32 v202, 0xbfb8aa3b, v18
	v_mul_f32_e32 v203, 0xbfb8aa3b, v19
	v_exp_f32_e32 v202, v202
	v_exp_f32_e32 v203, v203
	v_cvt_pk_bf16_f32 v214, v216, v215
	v_pk_add_f32 v[202:203], v[202:203], 1.0 op_sel_hi:[1,0]
	s_nop 0
	v_rcp_f32_e32 v203, v203
	v_rcp_f32_e32 v202, v202
	s_nop 0
	v_cvt_pk_bf16_f32 v215, v202, v203
	global_store_dwordx4 v[178:179], v[212:215], off offset:256
	v_add_u32_e32 v178, s22, v192
	v_ashrrev_i32_e32 v179, 31, v178
	v_lshlrev_b64 v[178:179], 11, v[178:179]
	v_lshl_add_u64 v[178:179], s[28:29], 0, v[178:179]
	v_lshl_add_u64 v[178:179], v[178:179], 0, s[38:39]
	v_lshl_add_u64 v[178:179], v[178:179], 0, v[184:185]
	v_mul_f32_e32 v184, 0xbfb8aa3b, v12
	v_exp_f32_e32 v202, v184
	v_mul_f32_e32 v184, 0xbfb8aa3b, v13
	v_exp_f32_e32 v203, v184
	s_nop 0
	v_pk_add_f32 v[202:203], v[202:203], 1.0 op_sel_hi:[1,0]
	s_nop 0
	v_rcp_f32_e32 v184, v203
	v_rcp_f32_e32 v201, v202
	v_mul_f32_e32 v202, 0xbfb8aa3b, v14
	v_mul_f32_e32 v203, 0xbfb8aa3b, v15
	v_exp_f32_e32 v202, v202
	v_exp_f32_e32 v203, v203
	s_nop 0
	v_pk_add_f32 v[202:203], v[202:203], 1.0 op_sel_hi:[1,0]
	s_nop 0
	v_rcp_f32_e32 v213, v203
	v_rcp_f32_e32 v214, v202
	v_mul_f32_e32 v202, 0xbfb8aa3b, v8
	v_mul_f32_e32 v203, 0xbfb8aa3b, v9
	v_exp_f32_e32 v202, v202
	v_exp_f32_e32 v203, v203
	v_cvt_pk_bf16_f32 v213, v214, v213
	v_pk_add_f32 v[202:203], v[202:203], 1.0 op_sel_hi:[1,0]
	s_nop 0
	v_rcp_f32_e32 v215, v203
	v_rcp_f32_e32 v216, v202
	v_mul_f32_e32 v202, 0xbfb8aa3b, v10
	v_mul_f32_e32 v203, 0xbfb8aa3b, v11
	v_exp_f32_e32 v202, v202
	v_exp_f32_e32 v203, v203
	v_cvt_pk_bf16_f32 v214, v216, v215
	v_pk_add_f32 v[202:203], v[202:203], 1.0 op_sel_hi:[1,0]
	s_nop 0
	v_rcp_f32_e32 v203, v203
	v_rcp_f32_e32 v202, v202
	v_cvt_pk_bf16_f32 v212, v201, v184
	v_mul_f32_e32 v184, 0xbfb8aa3b, v4
	v_cvt_pk_bf16_f32 v215, v202, v203
	v_exp_f32_e32 v202, v184
	v_mul_f32_e32 v184, 0xbfb8aa3b, v5
	v_exp_f32_e32 v203, v184
	global_store_dwordx4 v[178:179], v[212:215], off
	v_pk_add_f32 v[202:203], v[202:203], 1.0 op_sel_hi:[1,0]
	s_nop 0
	v_rcp_f32_e32 v184, v203
	v_rcp_f32_e32 v201, v202
	v_mul_f32_e32 v202, 0xbfb8aa3b, v6
	v_mul_f32_e32 v203, 0xbfb8aa3b, v7
	v_exp_f32_e32 v202, v202
	v_exp_f32_e32 v203, v203
	s_nop 0
	v_pk_add_f32 v[202:203], v[202:203], 1.0 op_sel_hi:[1,0]
	s_nop 0
	v_rcp_f32_e32 v213, v203
	v_rcp_f32_e32 v214, v202
	v_mul_f32_e32 v202, 0xbfb8aa3b, v0
	v_mul_f32_e32 v203, 0xbfb8aa3b, v1
	v_exp_f32_e32 v202, v202
	v_exp_f32_e32 v203, v203
	v_cvt_pk_bf16_f32 v213, v214, v213
	v_pk_add_f32 v[202:203], v[202:203], 1.0 op_sel_hi:[1,0]
	s_nop 0
	v_rcp_f32_e32 v215, v203
	v_rcp_f32_e32 v216, v202
	v_mul_f32_e32 v202, 0xbfb8aa3b, v2
	v_mul_f32_e32 v203, 0xbfb8aa3b, v3
	v_exp_f32_e32 v202, v202
	v_exp_f32_e32 v203, v203
	v_cvt_pk_bf16_f32 v214, v216, v215
	v_pk_add_f32 v[202:203], v[202:203], 1.0 op_sel_hi:[1,0]
	s_nop 0
	v_rcp_f32_e32 v203, v203
	s_mov_b64 s[22:23], 0
	v_rcp_f32_e32 v202, v202
	v_cvt_pk_bf16_f32 v212, v201, v184
	v_cvt_pk_bf16_f32 v215, v202, v203
	global_store_dwordx4 v[178:179], v[212:215], off offset:256
; __device__ __forceinline__ unsigned pk2(float lo, float hi) { f32x2 v = {lo, hi}; bf16x2_hw b = __builtin_convertvector(v, bf16x2_hw); return __builtin_bit_cast(unsigned, b); }
; __device__ __forceinline__ float sigm(float x) { return 1.f / (1.f + __expf(-x)); }
; __device__ __forceinline__ void st_bf8(bf16* p, f32x4 a, f32x4 b) { u32x4 w; w.x = pk2(a[0], a[1]); w.y = pk2(a[2], a[3]); w.z = pk2(b[0], b[1]); w.w = pk2(b[2], b[3]); *(u32x4*)p = w; }
; __device__ __forceinline__ void ld_bf8(const bf16* p, f32x4& a, f32x4& b) { const u32x4 w = *(const u32x4*)p; a = (f32x4){bflo(w.x), bfhi(w.x), bflo(w.y), bfhi(w.y)}; b = (f32x4){bflo(w.z), bfhi(w.z), bflo(w.w), bfhi(w.w)}; }
; __device__ __forceinline__ f32x4 sigm4(f32x4 v) { return (f32x4){sigm(v[0]), sigm(v[1]), sigm(v[2]), sigm(v[3])}; }
;     __device__ __forceinline__ void operator()(AccRef acc, const pg8::Unit& u, int wr, int wc, int fr, int fq) const {
;     ...
;         else if (t < 19) { const int c0 = (t - 15) * 256; EPI_LOOP_P( st_bf8(GD + rw * 1024 + c0 + cl, sigm4(v0), sigm4(v1)); ) }
;         else { const int c0 = (t - 19) * 256; EPI_LOOP_P( st_bf8(GM + rw * 1024 + c0 + cl, sigm4(v0), sigm4(v1)); ) }
.LBB0_797:
	s_andn2_b64 vcc, exec, s[22:23]
	s_cbranch_vccnz .LBB0_799
	s_lshl_b32 s22, s74, 8
	v_add_u32_e32 v178, s22, v145
	v_ashrrev_i32_e32 v179, 31, v178
	v_lshlrev_b64 v[178:179], 11, v[178:179]
	v_lshl_add_u64 v[178:179], s[26:27], 0, v[178:179]
	s_lshl_b64 s[38:39], s[66:67], 1
	s_movk_i32 s88, 0xe200
	v_lshl_add_u64 v[178:179], v[178:179], 0, s[38:39]
	s_mov_b32 s89, -1
	v_lshl_add_u64 v[178:179], v[178:179], 0, s[88:89]
	v_lshlrev_b32_e32 v184, 1, v144
	v_lshl_add_u64 v[202:203], v[178:179], 0, v[184:185]
	global_store_dwordx4 v[202:203], v[128:131], off
	s_nop 1
	s_nop 1
	v_lshlrev_b32_e32 v128, 1, v146
	v_mov_b32_e32 v129, v185
	v_lshl_add_u64 v[130:131], v[178:179], 0, v[128:129]
	global_store_dwordx4 v[130:131], v[132:135], off
	v_add_u32_e32 v130, s22, v180
	v_ashrrev_i32_e32 v131, 31, v130
	v_pk_add_f32 v[134:135], v[176:177], 1.0 op_sel_hi:[1,0]
	v_lshlrev_b64 v[130:131], 11, v[130:131]
	v_lshl_add_u64 v[130:131], s[26:27], 0, v[130:131]
	v_lshl_add_u64 v[130:131], v[130:131], 0, s[38:39]
	v_lshl_add_u64 v[130:131], v[130:131], 0, s[88:89]
	v_rcp_f32_e32 v176, v135
	v_lshl_add_u64 v[132:133], v[130:131], 0, v[184:185]
	v_lshl_add_u64 v[130:131], v[130:131], 0, v[128:129]
	v_rcp_f32_e32 v177, v134
	v_pk_add_f32 v[134:135], v[174:175], 1.0 op_sel_hi:[1,0]
	s_nop 0
	v_rcp_f32_e32 v174, v135
	v_rcp_f32_e32 v175, v134
	v_pk_add_f32 v[134:135], v[172:173], 1.0 op_sel_hi:[1,0]
	s_nop 0
	v_rcp_f32_e32 v172, v135
	v_rcp_f32_e32 v173, v134
	v_pk_add_f32 v[134:135], v[170:171], 1.0 op_sel_hi:[1,0]
	v_cvt_pk_bf16_f32 v172, v173, v172
	v_rcp_f32_e32 v135, v135
	v_rcp_f32_e32 v134, v134
	v_cvt_pk_bf16_f32 v170, v177, v176
	v_cvt_pk_bf16_f32 v171, v175, v174
	v_cvt_pk_bf16_f32 v173, v134, v135
	global_store_dwordx4 v[132:133], v[170:173], off
	v_pk_add_f32 v[132:133], v[168:169], 1.0 op_sel_hi:[1,0]
	s_nop 0
	v_rcp_f32_e32 v134, v133
	v_rcp_f32_e32 v135, v132
	v_pk_add_f32 v[132:133], v[166:167], 1.0 op_sel_hi:[1,0]
	s_nop 0
	v_rcp_f32_e32 v166, v133
	v_rcp_f32_e32 v167, v132
	v_pk_add_f32 v[132:133], v[164:165], 1.0 op_sel_hi:[1,0]
	s_nop 0
	v_rcp_f32_e32 v164, v133
	v_rcp_f32_e32 v165, v132
	v_pk_add_f32 v[132:133], v[162:163], 1.0 op_sel_hi:[1,0]
	s_nop 0
	v_rcp_f32_e32 v162, v133
	v_rcp_f32_e32 v163, v132
	v_cvt_pk_bf16_f32 v132, v135, v134
	v_cvt_pk_bf16_f32 v133, v167, v166
	v_cvt_pk_bf16_f32 v134, v165, v164
	v_cvt_pk_bf16_f32 v135, v163, v162
	global_store_dwordx4 v[130:131], v[132:135], off
	v_add_u32_e32 v130, s22, v181
	v_ashrrev_i32_e32 v131, 31, v130
	v_pk_add_f32 v[134:135], v[160:161], 1.0 op_sel_hi:[1,0]
	v_lshlrev_b64 v[130:131], 11, v[130:131]
	v_lshl_add_u64 v[130:131], s[26:27], 0, v[130:131]
	v_lshl_add_u64 v[130:131], v[130:131], 0, s[38:39]
	v_lshl_add_u64 v[130:131], v[130:131], 0, s[88:89]
	v_rcp_f32_e32 v160, v135
	v_lshl_add_u64 v[132:133], v[130:131], 0, v[184:185]
	v_lshl_add_u64 v[130:131], v[130:131], 0, v[128:129]
	v_rcp_f32_e32 v161, v134
	v_pk_add_f32 v[134:135], v[158:159], 1.0 op_sel_hi:[1,0]
	s_nop 0
	v_rcp_f32_e32 v158, v135
	v_rcp_f32_e32 v159, v134
	v_pk_add_f32 v[134:135], v[156:157], 1.0 op_sel_hi:[1,0]
	s_nop 0
	v_rcp_f32_e32 v156, v135
	v_rcp_f32_e32 v157, v134
	v_pk_add_f32 v[134:135], v[154:155], 1.0 op_sel_hi:[1,0]
	v_cvt_pk_bf16_f32 v156, v157, v156
	v_rcp_f32_e32 v135, v135
	v_rcp_f32_e32 v134, v134
	v_cvt_pk_bf16_f32 v154, v161, v160
	v_cvt_pk_bf16_f32 v155, v159, v158
	v_cvt_pk_bf16_f32 v157, v134, v135
	global_store_dwordx4 v[132:133], v[154:157], off
	v_pk_add_f32 v[132:133], v[152:153], 1.0 op_sel_hi:[1,0]
	s_nop 0
	v_rcp_f32_e32 v134, v133
	v_rcp_f32_e32 v135, v132
	v_exp_f32_e32 v132, v199
	v_exp_f32_e32 v133, v200
	s_nop 0
	v_pk_add_f32 v[132:133], v[132:133], 1.0 op_sel_hi:[1,0]
	s_nop 0
	v_rcp_f32_e32 v152, v133
	v_rcp_f32_e32 v153, v132
	v_exp_f32_e32 v132, v197
	v_exp_f32_e32 v133, v198
	s_nop 0
	v_pk_add_f32 v[132:133], v[132:133], 1.0 op_sel_hi:[1,0]
	s_nop 0
	v_rcp_f32_e32 v154, v133
	v_rcp_f32_e32 v155, v132
	v_exp_f32_e32 v132, v194
	v_exp_f32_e32 v133, v196
	s_nop 0
	v_pk_add_f32 v[132:133], v[132:133], 1.0 op_sel_hi:[1,0]
	s_nop 0
	v_rcp_f32_e32 v156, v133
	v_rcp_f32_e32 v157, v132
	v_cvt_pk_bf16_f32 v132, v135, v134
	v_cvt_pk_bf16_f32 v133, v153, v152
	v_cvt_pk_bf16_f32 v134, v155, v154
	v_cvt_pk_bf16_f32 v135, v157, v156
	global_store_dwordx4 v[130:131], v[132:135], off
	v_add_u32_e32 v130, s22, v182
	v_ashrrev_i32_e32 v131, 31, v130
	v_mul_f32_e32 v134, 0xbfb8aa3b, v76
	v_mul_f32_e32 v135, 0xbfb8aa3b, v77
	v_exp_f32_e32 v134, v134
	v_exp_f32_e32 v135, v135
	v_lshlrev_b64 v[130:131], 11, v[130:131]
	v_lshl_add_u64 v[130:131], s[26:27], 0, v[130:131]
	v_lshl_add_u64 v[130:131], v[130:131], 0, s[38:39]
	v_pk_add_f32 v[134:135], v[134:135], 1.0 op_sel_hi:[1,0]
	v_lshl_add_u64 v[130:131], v[130:131], 0, s[88:89]
	v_lshl_add_u64 v[132:133], v[130:131], 0, v[184:185]
	v_lshl_add_u64 v[130:131], v[130:131], 0, v[128:129]
	v_rcp_f32_e32 v152, v135
	v_rcp_f32_e32 v153, v134
	v_mul_f32_e32 v134, 0xbfb8aa3b, v78
	v_mul_f32_e32 v135, 0xbfb8aa3b, v79
	v_exp_f32_e32 v134, v134
	v_exp_f32_e32 v135, v135
	v_cvt_pk_bf16_f32 v152, v153, v152
	v_pk_add_f32 v[134:135], v[134:135], 1.0 op_sel_hi:[1,0]
	s_nop 0
	v_rcp_f32_e32 v154, v135
	v_rcp_f32_e32 v155, v134
	v_mul_f32_e32 v134, 0xbfb8aa3b, v72
	v_mul_f32_e32 v135, 0xbfb8aa3b, v73
	v_exp_f32_e32 v134, v134
	v_exp_f32_e32 v135, v135
	v_cvt_pk_bf16_f32 v153, v155, v154
	v_pk_add_f32 v[134:135], v[134:135], 1.0 op_sel_hi:[1,0]
	s_nop 0
	v_rcp_f32_e32 v156, v135
	v_rcp_f32_e32 v157, v134
	v_mul_f32_e32 v134, 0xbfb8aa3b, v74
	v_mul_f32_e32 v135, 0xbfb8aa3b, v75
	v_exp_f32_e32 v134, v134
	v_exp_f32_e32 v135, v135
	v_cvt_pk_bf16_f32 v154, v157, v156
; __device__ __forceinline__ unsigned pk2(float lo, float hi) { f32x2 v = {lo, hi}; bf16x2_hw b = __builtin_convertvector(v, bf16x2_hw); return __builtin_bit_cast(unsigned, b); }
; __device__ __forceinline__ float sigm(float x) { return 1.f / (1.f + __expf(-x)); }
; __device__ __forceinline__ void st_bf8(bf16* p, f32x4 a, f32x4 b) { u32x4 w; w.x = pk2(a[0], a[1]); w.y = pk2(a[2], a[3]); w.z = pk2(b[0], b[1]); w.w = pk2(b[2], b[3]); *(u32x4*)p = w; }
; __device__ __forceinline__ void ld_bf8(const bf16* p, f32x4& a, f32x4& b) { const u32x4 w = *(const u32x4*)p; a = (f32x4){bflo(w.x), bfhi(w.x), bflo(w.y), bfhi(w.y)}; b = (f32x4){bflo(w.z), bfhi(w.z), bflo(w.w), bfhi(w.w)}; }
; __device__ __forceinline__ f32x4 sigm4(f32x4 v) { return (f32x4){sigm(v[0]), sigm(v[1]), sigm(v[2]), sigm(v[3])}; }
;     __device__ __forceinline__ void operator()(AccRef acc, const pg8::Unit& u, int wr, int wc, int fr, int fq) const {
;     ...
;         else if (t < 19) { const int c0 = (t - 15) * 256; EPI_LOOP_P( st_bf8(GD + rw * 1024 + c0 + cl, sigm4(v0), sigm4(v1)); ) }
;         else { const int c0 = (t - 19) * 256; EPI_LOOP_P( st_bf8(GM + rw * 1024 + c0 + cl, sigm4(v0), sigm4(v1)); ) }
	v_pk_add_f32 v[134:135], v[134:135], 1.0 op_sel_hi:[1,0]
	s_nop 0
	v_rcp_f32_e32 v135, v135
	v_rcp_f32_e32 v134, v134
	s_nop 0
	v_cvt_pk_bf16_f32 v155, v134, v135
	global_store_dwordx4 v[132:133], v[152:155], off
	v_mul_f32_e32 v132, 0xbfb8aa3b, v68
	v_mul_f32_e32 v133, 0xbfb8aa3b, v69
	v_exp_f32_e32 v132, v132
	v_exp_f32_e32 v133, v133
	s_nop 0
	v_pk_add_f32 v[132:133], v[132:133], 1.0 op_sel_hi:[1,0]
	s_nop 0
	v_rcp_f32_e32 v134, v133
	v_rcp_f32_e32 v135, v132
	v_mul_f32_e32 v132, 0xbfb8aa3b, v70
	v_mul_f32_e32 v133, 0xbfb8aa3b, v71
	v_exp_f32_e32 v132, v132
	v_exp_f32_e32 v133, v133
	s_nop 0
	v_pk_add_f32 v[132:133], v[132:133], 1.0 op_sel_hi:[1,0]
	s_nop 0
	v_rcp_f32_e32 v152, v133
	v_rcp_f32_e32 v153, v132
	v_mul_f32_e32 v132, 0xbfb8aa3b, v64
	v_mul_f32_e32 v133, 0xbfb8aa3b, v65
	v_exp_f32_e32 v132, v132
	v_exp_f32_e32 v133, v133
	s_nop 0
	v_pk_add_f32 v[132:133], v[132:133], 1.0 op_sel_hi:[1,0]
	s_nop 0
	v_rcp_f32_e32 v154, v133
	v_rcp_f32_e32 v155, v132
	v_mul_f32_e32 v132, 0xbfb8aa3b, v66
	v_mul_f32_e32 v133, 0xbfb8aa3b, v67
	v_exp_f32_e32 v132, v132
	v_exp_f32_e32 v133, v133
	s_nop 0
	v_pk_add_f32 v[132:133], v[132:133], 1.0 op_sel_hi:[1,0]
	s_nop 0
	v_rcp_f32_e32 v156, v133
	v_rcp_f32_e32 v157, v132
	v_cvt_pk_bf16_f32 v132, v135, v134
	v_cvt_pk_bf16_f32 v133, v153, v152
	v_cvt_pk_bf16_f32 v134, v155, v154
	v_cvt_pk_bf16_f32 v135, v157, v156
	global_store_dwordx4 v[130:131], v[132:135], off
	v_add_u32_e32 v130, s22, v183
	v_ashrrev_i32_e32 v131, 31, v130
	v_mul_f32_e32 v134, 0xbfb8aa3b, v60
	v_mul_f32_e32 v135, 0xbfb8aa3b, v61
	v_exp_f32_e32 v134, v134
	v_exp_f32_e32 v135, v135
	v_lshlrev_b64 v[130:131], 11, v[130:131]
	v_lshl_add_u64 v[130:131], s[26:27], 0, v[130:131]
	v_lshl_add_u64 v[130:131], v[130:131], 0, s[38:39]
	v_pk_add_f32 v[134:135], v[134:135], 1.0 op_sel_hi:[1,0]
	v_lshl_add_u64 v[130:131], v[130:131], 0, s[88:89]
	v_lshl_add_u64 v[132:133], v[130:131], 0, v[184:185]
	v_lshl_add_u64 v[130:131], v[130:131], 0, v[128:129]
	v_rcp_f32_e32 v152, v135
	v_rcp_f32_e32 v153, v134
	v_mul_f32_e32 v134, 0xbfb8aa3b, v62
	v_mul_f32_e32 v135, 0xbfb8aa3b, v63
	v_exp_f32_e32 v134, v134
	v_exp_f32_e32 v135, v135
	v_cvt_pk_bf16_f32 v152, v153, v152
	v_pk_add_f32 v[134:135], v[134:135], 1.0 op_sel_hi:[1,0]
	s_nop 0
	v_rcp_f32_e32 v154, v135
	v_rcp_f32_e32 v155, v134
	v_mul_f32_e32 v134, 0xbfb8aa3b, v56
	v_mul_f32_e32 v135, 0xbfb8aa3b, v57
	v_exp_f32_e32 v134, v134
	v_exp_f32_e32 v135, v135
	v_cvt_pk_bf16_f32 v153, v155, v154
	v_pk_add_f32 v[134:135], v[134:135], 1.0 op_sel_hi:[1,0]
	s_nop 0
	v_rcp_f32_e32 v156, v135
	v_rcp_f32_e32 v157, v134
	v_mul_f32_e32 v134, 0xbfb8aa3b, v58
	v_mul_f32_e32 v135, 0xbfb8aa3b, v59
	v_exp_f32_e32 v134, v134
	v_exp_f32_e32 v135, v135
	v_cvt_pk_bf16_f32 v154, v157, v156
	v_pk_add_f32 v[134:135], v[134:135], 1.0 op_sel_hi:[1,0]
	s_nop 0
	v_rcp_f32_e32 v135, v135
	v_rcp_f32_e32 v134, v134
	s_nop 0
	v_cvt_pk_bf16_f32 v155, v134, v135
	global_store_dwordx4 v[132:133], v[152:155], off
	v_mul_f32_e32 v132, 0xbfb8aa3b, v52
	v_mul_f32_e32 v133, 0xbfb8aa3b, v53
	v_exp_f32_e32 v132, v132
	v_exp_f32_e32 v133, v133
	s_nop 0
	v_pk_add_f32 v[132:133], v[132:133], 1.0 op_sel_hi:[1,0]
	s_nop 0
	v_rcp_f32_e32 v134, v133
	v_rcp_f32_e32 v135, v132
	v_mul_f32_e32 v132, 0xbfb8aa3b, v54
	v_mul_f32_e32 v133, 0xbfb8aa3b, v55
	v_exp_f32_e32 v132, v132
	v_exp_f32_e32 v133, v133
	s_nop 0
	v_pk_add_f32 v[132:133], v[132:133], 1.0 op_sel_hi:[1,0]
	s_nop 0
	v_rcp_f32_e32 v152, v133
	v_rcp_f32_e32 v153, v132
	v_mul_f32_e32 v132, 0xbfb8aa3b, v48
	v_mul_f32_e32 v133, 0xbfb8aa3b, v49
	v_exp_f32_e32 v132, v132
	v_exp_f32_e32 v133, v133
	s_nop 0
	v_pk_add_f32 v[132:133], v[132:133], 1.0 op_sel_hi:[1,0]
	s_nop 0
	v_rcp_f32_e32 v154, v133
	v_rcp_f32_e32 v155, v132
	v_mul_f32_e32 v132, 0xbfb8aa3b, v50
	v_mul_f32_e32 v133, 0xbfb8aa3b, v51
	v_exp_f32_e32 v132, v132
	v_exp_f32_e32 v133, v133
	s_nop 0
	v_pk_add_f32 v[132:133], v[132:133], 1.0 op_sel_hi:[1,0]
	s_nop 0
	v_rcp_f32_e32 v156, v133
	v_rcp_f32_e32 v157, v132
	v_cvt_pk_bf16_f32 v132, v135, v134
	v_cvt_pk_bf16_f32 v133, v153, v152
	v_cvt_pk_bf16_f32 v134, v155, v154
	v_cvt_pk_bf16_f32 v135, v157, v156
	global_store_dwordx4 v[130:131], v[132:135], off
	v_add_u32_e32 v130, s22, v190
	v_ashrrev_i32_e32 v131, 31, v130
	v_mul_f32_e32 v134, 0xbfb8aa3b, v44
	v_mul_f32_e32 v135, 0xbfb8aa3b, v45
	v_exp_f32_e32 v134, v134
	v_exp_f32_e32 v135, v135
	v_lshlrev_b64 v[130:131], 11, v[130:131]
	v_lshl_add_u64 v[130:131], s[26:27], 0, v[130:131]
	v_lshl_add_u64 v[130:131], v[130:131], 0, s[38:39]
	v_pk_add_f32 v[134:135], v[134:135], 1.0 op_sel_hi:[1,0]
	v_lshl_add_u64 v[130:131], v[130:131], 0, s[88:89]
	v_lshl_add_u64 v[132:133], v[130:131], 0, v[184:185]
	v_lshl_add_u64 v[130:131], v[130:131], 0, v[128:129]
	v_rcp_f32_e32 v152, v135
	v_rcp_f32_e32 v153, v134
	v_mul_f32_e32 v134, 0xbfb8aa3b, v46
	v_mul_f32_e32 v135, 0xbfb8aa3b, v47
	v_exp_f32_e32 v134, v134
	v_exp_f32_e32 v135, v135
	v_cvt_pk_bf16_f32 v152, v153, v152
	v_pk_add_f32 v[134:135], v[134:135], 1.0 op_sel_hi:[1,0]
	s_nop 0
	v_rcp_f32_e32 v154, v135
	v_rcp_f32_e32 v155, v134
	v_mul_f32_e32 v134, 0xbfb8aa3b, v40
	v_mul_f32_e32 v135, 0xbfb8aa3b, v41
	v_exp_f32_e32 v134, v134
	v_exp_f32_e32 v135, v135
	v_cvt_pk_bf16_f32 v153, v155, v154
	v_pk_add_f32 v[134:135], v[134:135], 1.0 op_sel_hi:[1,0]
	s_nop 0
	v_rcp_f32_e32 v156, v135
	v_rcp_f32_e32 v157, v134
	v_mul_f32_e32 v134, 0xbfb8aa3b, v42
	v_mul_f32_e32 v135, 0xbfb8aa3b, v43
	v_exp_f32_e32 v134, v134
	v_exp_f32_e32 v135, v135
	v_cvt_pk_bf16_f32 v154, v157, v156
	v_pk_add_f32 v[134:135], v[134:135], 1.0 op_sel_hi:[1,0]
	s_nop 0
	v_rcp_f32_e32 v135, v135
	v_rcp_f32_e32 v134, v134
	s_nop 0
; __device__ __forceinline__ unsigned pk2(float lo, float hi) { f32x2 v = {lo, hi}; bf16x2_hw b = __builtin_convertvector(v, bf16x2_hw); return __builtin_bit_cast(unsigned, b); }
; __device__ __forceinline__ float sigm(float x) { return 1.f / (1.f + __expf(-x)); }
; __device__ __forceinline__ void st_bf8(bf16* p, f32x4 a, f32x4 b) { u32x4 w; w.x = pk2(a[0], a[1]); w.y = pk2(a[2], a[3]); w.z = pk2(b[0], b[1]); w.w = pk2(b[2], b[3]); *(u32x4*)p = w; }
; __device__ __forceinline__ void ld_bf8(const bf16* p, f32x4& a, f32x4& b) { const u32x4 w = *(const u32x4*)p; a = (f32x4){bflo(w.x), bfhi(w.x), bflo(w.y), bfhi(w.y)}; b = (f32x4){bflo(w.z), bfhi(w.z), bflo(w.w), bfhi(w.w)}; }
; __device__ __forceinline__ f32x4 sigm4(f32x4 v) { return (f32x4){sigm(v[0]), sigm(v[1]), sigm(v[2]), sigm(v[3])}; }
;     __device__ __forceinline__ void operator()(AccRef acc, const pg8::Unit& u, int wr, int wc, int fr, int fq) const {
;     ...
;         else if (t < 19) { const int c0 = (t - 15) * 256; EPI_LOOP_P( st_bf8(GD + rw * 1024 + c0 + cl, sigm4(v0), sigm4(v1)); ) }
;         else { const int c0 = (t - 19) * 256; EPI_LOOP_P( st_bf8(GM + rw * 1024 + c0 + cl, sigm4(v0), sigm4(v1)); ) }
	v_cvt_pk_bf16_f32 v155, v134, v135
	global_store_dwordx4 v[132:133], v[152:155], off
	v_mul_f32_e32 v132, 0xbfb8aa3b, v36
	v_mul_f32_e32 v133, 0xbfb8aa3b, v37
	v_exp_f32_e32 v132, v132
	v_exp_f32_e32 v133, v133
	s_nop 0
	v_pk_add_f32 v[132:133], v[132:133], 1.0 op_sel_hi:[1,0]
	s_nop 0
	v_rcp_f32_e32 v134, v133
	v_rcp_f32_e32 v135, v132
	v_mul_f32_e32 v132, 0xbfb8aa3b, v38
	v_mul_f32_e32 v133, 0xbfb8aa3b, v39
	v_exp_f32_e32 v132, v132
	v_exp_f32_e32 v133, v133
	s_nop 0
	v_pk_add_f32 v[132:133], v[132:133], 1.0 op_sel_hi:[1,0]
	s_nop 0
	v_rcp_f32_e32 v152, v133
	v_rcp_f32_e32 v153, v132
	v_mul_f32_e32 v132, 0xbfb8aa3b, v32
	v_mul_f32_e32 v133, 0xbfb8aa3b, v33
	v_exp_f32_e32 v132, v132
	v_exp_f32_e32 v133, v133
	s_nop 0
	v_pk_add_f32 v[132:133], v[132:133], 1.0 op_sel_hi:[1,0]
	s_nop 0
	v_rcp_f32_e32 v154, v133
	v_rcp_f32_e32 v155, v132
	v_mul_f32_e32 v132, 0xbfb8aa3b, v34
	v_mul_f32_e32 v133, 0xbfb8aa3b, v35
	v_exp_f32_e32 v132, v132
	v_exp_f32_e32 v133, v133
	s_nop 0
	v_pk_add_f32 v[132:133], v[132:133], 1.0 op_sel_hi:[1,0]
	s_nop 0
	v_rcp_f32_e32 v156, v133
	v_rcp_f32_e32 v157, v132
	v_cvt_pk_bf16_f32 v132, v135, v134
	v_cvt_pk_bf16_f32 v133, v153, v152
	v_cvt_pk_bf16_f32 v134, v155, v154
	v_cvt_pk_bf16_f32 v135, v157, v156
	global_store_dwordx4 v[130:131], v[132:135], off
	v_add_u32_e32 v130, s22, v191
	v_ashrrev_i32_e32 v131, 31, v130
	v_mul_f32_e32 v134, 0xbfb8aa3b, v28
	v_mul_f32_e32 v135, 0xbfb8aa3b, v29
	v_exp_f32_e32 v134, v134
	v_exp_f32_e32 v135, v135
	v_lshlrev_b64 v[130:131], 11, v[130:131]
	v_lshl_add_u64 v[130:131], s[26:27], 0, v[130:131]
	v_lshl_add_u64 v[130:131], v[130:131], 0, s[38:39]
	v_pk_add_f32 v[134:135], v[134:135], 1.0 op_sel_hi:[1,0]
	v_lshl_add_u64 v[130:131], v[130:131], 0, s[88:89]
	v_lshl_add_u64 v[132:133], v[130:131], 0, v[184:185]
	v_lshl_add_u64 v[130:131], v[130:131], 0, v[128:129]
	v_rcp_f32_e32 v152, v135
	v_rcp_f32_e32 v153, v134
	v_mul_f32_e32 v134, 0xbfb8aa3b, v30
	v_mul_f32_e32 v135, 0xbfb8aa3b, v31
	v_exp_f32_e32 v134, v134
	v_exp_f32_e32 v135, v135
	v_cvt_pk_bf16_f32 v152, v153, v152
	v_pk_add_f32 v[134:135], v[134:135], 1.0 op_sel_hi:[1,0]
	s_nop 0
	v_rcp_f32_e32 v154, v135
	v_rcp_f32_e32 v155, v134
	v_mul_f32_e32 v134, 0xbfb8aa3b, v24
	v_mul_f32_e32 v135, 0xbfb8aa3b, v25
	v_exp_f32_e32 v134, v134
	v_exp_f32_e32 v135, v135
	v_cvt_pk_bf16_f32 v153, v155, v154
	v_pk_add_f32 v[134:135], v[134:135], 1.0 op_sel_hi:[1,0]
	s_nop 0
	v_rcp_f32_e32 v156, v135
	v_rcp_f32_e32 v157, v134
	v_mul_f32_e32 v134, 0xbfb8aa3b, v26
	v_mul_f32_e32 v135, 0xbfb8aa3b, v27
	v_exp_f32_e32 v134, v134
	v_exp_f32_e32 v135, v135
	v_cvt_pk_bf16_f32 v154, v157, v156
	v_pk_add_f32 v[134:135], v[134:135], 1.0 op_sel_hi:[1,0]
	s_nop 0
	v_rcp_f32_e32 v135, v135
	v_rcp_f32_e32 v134, v134
	s_nop 0
	v_cvt_pk_bf16_f32 v155, v134, v135
	global_store_dwordx4 v[132:133], v[152:155], off
	v_mul_f32_e32 v132, 0xbfb8aa3b, v20
	v_mul_f32_e32 v133, 0xbfb8aa3b, v21
	v_exp_f32_e32 v132, v132
	v_exp_f32_e32 v133, v133
	s_nop 0
	v_pk_add_f32 v[132:133], v[132:133], 1.0 op_sel_hi:[1,0]
	s_nop 0
	v_rcp_f32_e32 v134, v133
	v_rcp_f32_e32 v135, v132
	v_mul_f32_e32 v132, 0xbfb8aa3b, v22
	v_mul_f32_e32 v133, 0xbfb8aa3b, v23
	v_exp_f32_e32 v132, v132
	v_exp_f32_e32 v133, v133
	s_nop 0
	v_pk_add_f32 v[132:133], v[132:133], 1.0 op_sel_hi:[1,0]
	s_nop 0
	v_rcp_f32_e32 v152, v133
	v_rcp_f32_e32 v153, v132
	v_mul_f32_e32 v132, 0xbfb8aa3b, v16
	v_mul_f32_e32 v133, 0xbfb8aa3b, v17
	v_exp_f32_e32 v132, v132
	v_exp_f32_e32 v133, v133
	s_nop 0
	v_pk_add_f32 v[132:133], v[132:133], 1.0 op_sel_hi:[1,0]
	s_nop 0
	v_rcp_f32_e32 v154, v133
	v_rcp_f32_e32 v155, v132
	v_mul_f32_e32 v132, 0xbfb8aa3b, v18
	v_mul_f32_e32 v133, 0xbfb8aa3b, v19
	v_exp_f32_e32 v132, v132
	v_exp_f32_e32 v133, v133
	s_nop 0
	v_pk_add_f32 v[132:133], v[132:133], 1.0 op_sel_hi:[1,0]
	s_nop 0
	v_rcp_f32_e32 v156, v133
	v_rcp_f32_e32 v157, v132
	v_cvt_pk_bf16_f32 v132, v135, v134
	v_cvt_pk_bf16_f32 v133, v153, v152
	v_cvt_pk_bf16_f32 v134, v155, v154
	v_cvt_pk_bf16_f32 v135, v157, v156
	global_store_dwordx4 v[130:131], v[132:135], off
	v_add_u32_e32 v130, s22, v192
	v_ashrrev_i32_e32 v131, 31, v130
	v_mul_f32_e32 v134, 0xbfb8aa3b, v12
	v_mul_f32_e32 v135, 0xbfb8aa3b, v13
	v_exp_f32_e32 v134, v134
	v_exp_f32_e32 v135, v135
	v_lshlrev_b64 v[130:131], 11, v[130:131]
	v_lshl_add_u64 v[130:131], s[26:27], 0, v[130:131]
	v_lshl_add_u64 v[130:131], v[130:131], 0, s[38:39]
	v_pk_add_f32 v[134:135], v[134:135], 1.0 op_sel_hi:[1,0]
	v_lshl_add_u64 v[130:131], v[130:131], 0, s[88:89]
	v_lshl_add_u64 v[132:133], v[130:131], 0, v[184:185]
	v_lshl_add_u64 v[128:129], v[130:131], 0, v[128:129]
	v_mul_f32_e32 v130, 0xbfb8aa3b, v4
	v_rcp_f32_e32 v152, v135
	v_mul_f32_e32 v131, 0xbfb8aa3b, v5
	v_exp_f32_e32 v130, v130
	v_exp_f32_e32 v131, v131
	v_rcp_f32_e32 v153, v134
	v_mul_f32_e32 v134, 0xbfb8aa3b, v14
	v_mul_f32_e32 v135, 0xbfb8aa3b, v15
	v_exp_f32_e32 v134, v134
	v_exp_f32_e32 v135, v135
	v_cvt_pk_bf16_f32 v152, v153, v152
	v_pk_add_f32 v[130:131], v[130:131], 1.0 op_sel_hi:[1,0]
	v_pk_add_f32 v[134:135], v[134:135], 1.0 op_sel_hi:[1,0]
	s_nop 0
	v_rcp_f32_e32 v154, v135
	v_rcp_f32_e32 v155, v134
	v_mul_f32_e32 v134, 0xbfb8aa3b, v8
	v_mul_f32_e32 v135, 0xbfb8aa3b, v9
	v_exp_f32_e32 v134, v134
	v_exp_f32_e32 v135, v135
	v_cvt_pk_bf16_f32 v153, v155, v154
	v_pk_add_f32 v[134:135], v[134:135], 1.0 op_sel_hi:[1,0]
	s_nop 0
	v_rcp_f32_e32 v156, v135
	v_rcp_f32_e32 v157, v134
	v_mul_f32_e32 v134, 0xbfb8aa3b, v10
	v_mul_f32_e32 v135, 0xbfb8aa3b, v11
	v_exp_f32_e32 v134, v134
	v_exp_f32_e32 v135, v135
	v_cvt_pk_bf16_f32 v154, v157, v156
	v_pk_add_f32 v[134:135], v[134:135], 1.0 op_sel_hi:[1,0]
	s_nop 0
	v_rcp_f32_e32 v135, v135
	v_rcp_f32_e32 v134, v134
	s_nop 0
	v_cvt_pk_bf16_f32 v155, v134, v135
	global_store_dwordx4 v[132:133], v[152:155], off
	v_rcp_f32_e32 v132, v131
	v_rcp_f32_e32 v133, v130
	v_mul_f32_e32 v130, 0xbfb8aa3b, v6
	v_mul_f32_e32 v131, 0xbfb8aa3b, v7
	v_exp_f32_e32 v130, v130
	v_exp_f32_e32 v131, v131
	s_nop 0
	v_pk_add_f32 v[130:131], v[130:131], 1.0 op_sel_hi:[1,0]
	s_nop 0
	v_rcp_f32_e32 v134, v131
	v_rcp_f32_e32 v135, v130
	v_mul_f32_e32 v130, 0xbfb8aa3b, v0
	v_mul_f32_e32 v131, 0xbfb8aa3b, v1
	v_exp_f32_e32 v130, v130
	v_exp_f32_e32 v131, v131
	s_nop 0
	v_pk_add_f32 v[130:131], v[130:131], 1.0 op_sel_hi:[1,0]
	s_nop 0
	v_rcp_f32_e32 v152, v131
	v_rcp_f32_e32 v153, v130
	v_mul_f32_e32 v130, 0xbfb8aa3b, v2
	v_mul_f32_e32 v131, 0xbfb8aa3b, v3
	v_exp_f32_e32 v130, v130
	v_exp_f32_e32 v131, v131
	s_nop 0
	v_pk_add_f32 v[130:131], v[130:131], 1.0 op_sel_hi:[1,0]
	s_nop 0
	v_rcp_f32_e32 v154, v131
	v_rcp_f32_e32 v155, v130
	v_cvt_pk_bf16_f32 v130, v133, v132
	v_cvt_pk_bf16_f32 v131, v135, v134
	v_cvt_pk_bf16_f32 v132, v153, v152
	v_cvt_pk_bf16_f32 v133, v155, v154
	global_store_dwordx4 v[128:129], v[130:133], off
